# attention: softmax reference subtraction folded into the QK product (one rank-1 bf16 MFMA per score tile with the bf16-exact negated reference; v_sub only in the rare reference-update path; first iter
# baseline (speedup 1.0000x reference)
; DEV int ltid() { int t = threadIdx.x; asm volatile("" : "+v"(t)); return t; }
; DEV void attn_tile(const Params& p, int l, int tile, char* smem, bool do_store = true) {
;     ...
;   const int tid = ltid(), lane = tid & 63, w = tid >> 6, ql = lane & 31, hh = lane >> 5, map = w >> 2, qg = w & 3;
;   const int qrow = qbase + q0 + qg * 32 + ql;
;   const float lam_init = l == 0 ? 0.2f : 0.35550907f;
;   float lam;
;   {
;     const float a1 = p.att_lq1[l * 64 + lane] * p.att_lk1[l * 64 + lane];
;     const float a2 = p.att_lq2[l * 64 + lane] * p.att_lk2[l * 64 + lane];
;     lam = __expf(wsum(a1)) - __expf(wsum(a2)) + lam_init;
;   }
;   bf16x8 qf[4];
; #pragma unroll
;   for (int s = 0; s < 4; ++s) qf[s] = *(const bf16x8*)(ZQ + (size_t)qrow * 512 + head * 128 + map * 64 + s * 16 + hh * 8);
;   f32x16 o[4];
; #pragma unroll
;   for (int dt = 0; dt < 4; ++dt)
; #pragma unroll
;     for (int e = 0; e < 16; ++e) o[dt][e] = 0.f;
;   float m = -1e30f, lsum = 0.f;
.LBB0_598:
	v_mov_b32_e32 v192, v226
	v_readlane_b32 s56, v254, 58
	v_readlane_b32 s57, v254, 59
	v_and_or_b32 v2, v192, 63, s96
	v_readlane_b32 s58, v254, 60
	v_readlane_b32 s59, v254, 61
	v_readlane_b32 s60, v254, 62
	v_readlane_b32 s61, v254, 63
	v_readlane_b32 s62, v255, 0
	v_readlane_b32 s63, v255, 1
	v_readlane_b32 s64, v255, 2
	v_readlane_b32 s65, v255, 3
	v_readlane_b32 s66, v255, 4
	v_readlane_b32 s67, v255, 5
	v_ashrrev_i32_e32 v3, 31, v2
	v_readlane_b32 s68, v255, 6
	v_readlane_b32 s69, v255, 7
	v_readlane_b32 s70, v255, 8
	v_readlane_b32 s71, v255, 9
	s_mov_b64 s[56:57], s[60:61]
	v_lshlrev_b64 v[2:3], 2, v[2:3]
	s_mov_b64 s[58:59], s[62:63]
	s_mov_b64 s[60:61], s[64:65]
	s_mov_b64 s[62:63], s[66:67]
	s_mov_b64 s[64:65], s[68:69]
	s_mov_b64 s[66:67], s[70:71]
	v_lshl_add_u64 v[4:5], s[64:65], 0, v[2:3]
	global_load_dword v1, v[4:5], off
	v_lshl_add_u64 v[4:5], s[66:67], 0, v[2:3]
	global_load_dword v6, v[4:5], off
	v_readlane_b32 s56, v251, 21
	v_readlane_b32 s57, v251, 22
	v_readlane_b32 s58, v251, 23
	v_readlane_b32 s59, v251, 24
	v_lshl_add_u64 v[4:5], s[56:57], 0, v[2:3]
	global_load_dword v4, v[4:5], off
	v_lshl_add_u64 v[2:3], s[58:59], 0, v[2:3]
	global_load_dword v2, v[2:3], off
	v_bfe_u32 v193, v192, 6, 2
	v_and_b32_e32 v194, 31, v192
	s_add_i32 s0, s38, s39
	v_lshlrev_b32_e32 v0, 5, v193
	v_add3_u32 v0, s0, v194, v0
	v_readlane_b32 s0, v252, 19
	v_readlane_b32 s1, v252, 20
	v_ashrrev_i32_e32 v195, 8, v192
	v_bfe_u32 v190, v192, 5, 1
	v_lshlrev_b32_e32 v96, 4, v190
	v_ashrrev_i32_e32 v200, 4, v192
	v_readlane_b32 s64, v251, 29
	v_readlane_b32 s65, v251, 30
	v_readlane_b32 s64, v255, 38
	v_readlane_b32 s52, v252, 21
	v_add_u32_e32 v14, 32, v200
	v_readlane_b32 s65, v255, 39
	v_readlane_b32 s53, v252, 22
	v_add_u32_e32 v22, 64, v200
	s_movk_i32 s41, 0x2200
	v_add_u32_e32 v32, 0x60, v200
	v_readlane_b32 s60, v251, 25
	v_readlane_b32 s61, v251, 26
	v_readlane_b32 s66, v251, 31
	v_readlane_b32 s67, v251, 32
	v_readlane_b32 s68, v251, 33
	v_readlane_b32 s69, v251, 34
	v_readlane_b32 s70, v251, 35
	v_readlane_b32 s71, v251, 36
	v_readlane_b32 s60, v255, 32
	v_readlane_b32 s66, v255, 34
	v_readlane_b32 s68, v255, 36
	v_lshrrev_b32_e32 v191, 6, v192
	v_lshl_or_b32 v204, v195, 7, v96
	v_mul_u32_u24_e32 v201, 0x110, v194
	v_mov_b32_e32 v209, 0
	v_mov_b32_e32 v208, 0
	v_mov_b32_e32 v250, 0
	v_and_b32_e32 v241, 63, v226
	v_cmp_gt_u32_e32 vcc, 32, v241
	v_mov_b32_e32 v241, 0x3f80
	v_mov_b32_e32 v245, 0
	v_cndmask_b32_e32 v244, 0, v241, vcc
	v_mov_b32_e32 v246, 0
	v_mov_b32_e32 v247, 0
	v_mov_b32_e32 v248, 0
	v_mov_b32_e32 v249, 0
	v_readlane_b32 s61, v255, 33
	v_readlane_b32 s67, v255, 35
	v_readlane_b32 s69, v255, 37
	v_readlane_b32 s70, v255, 41
	s_mov_b32 s71, 0x8000
	v_readlane_b32 s62, v251, 27
	v_readlane_b32 s63, v251, 28
	s_waitcnt vmcnt(2)
	v_mul_f32_e32 v7, v1, v6
	s_nop 1
	v_mov_b32_dpp v5, v7 quad_perm:[1,0,3,2] row_mask:0xf bank_mask:0xf bound_ctrl:1
	v_fmac_f32_e32 v5, v1, v6
	s_waitcnt vmcnt(0)
; DEV void attn_tile(const Params& p, int l, int tile, char* smem, bool do_store = true) {
;     ...
;   {
;     const float a1 = p.att_lq1[l * 64 + lane] * p.att_lk1[l * 64 + lane];
;     const float a2 = p.att_lq2[l * 64 + lane] * p.att_lk2[l * 64 + lane];
;     lam = __expf(wsum(a1)) - __expf(wsum(a2)) + lam_init;
;   }
;   bf16x8 qf[4];
; #pragma unroll
;   for (int s = 0; s < 4; ++s) qf[s] = *(const bf16x8*)(ZQ + (size_t)qrow * 512 + head * 128 + map * 64 + s * 16 + hh * 8);
;   f32x16 o[4];
; #pragma unroll
;   for (int dt = 0; dt < 4; ++dt)
; #pragma unroll
;     for (int e = 0; e < 16; ++e) o[dt][e] = 0.f;
;   float m = -1e30f, lsum = 0.f;
;   const int kr0 = tid >> 4, kch = tid & 15;
;   const int vr0 = tid >> 4, vch = tid & 15;
;   const bf16_t* vtb = VT + ((size_t)((b * 4 + head) * 128)) * TK;
;   u32x4 kreg[4], vreg[4];
;   auto gload = [&](int kt) {
;     const int k0 = kt * 128;
; #pragma unroll
;     for (int i = 0; i < 4; ++i) {
;       const int kidx = k0 + kr0 + 32 * i;
;       const int krow = kidx < CTXL ? T_LAT + b * CTXL + kidx : b * SEQ + kidx - CTXL;
;       kreg[i] = *(const u32x4*)(ZK + (size_t)krow * 512 + head * 128 + kch * 8);
;       vreg[i] = *(const u32x4*)(vtb + (size_t)(vr0 + 32 * i) * TK + k0 + vch * 8);
;     }
;   };
;   auto lstore = [&](int st) {
;     char* Ks = smem + st * ATT2_ST;
;     char* Vs = Ks + 128 * KROW;
; #pragma unroll
;     for (int i = 0; i < 4; ++i) {
;       *(u32x4*)(Ks + (kr0 + 32 * i) * KROW + kch * 16) = kreg[i];
;       *(u32x4*)(Vs + (vr0 + 32 * i) * KROW + vch * 16) = vreg[i];
;     }
;   };
;   const int nkt = nkeys >> 7;
;   gload(0);
;   __syncthreads();
;   lstore(0);
;   __syncthreads();
	v_mul_f32_e32 v3, v4, v2
	v_add_f32_dpp v1, v5, v5 quad_perm:[2,3,0,1] row_mask:0xf bank_mask:0xf bound_ctrl:1
	s_nop 1
	v_add_f32_dpp v1, v1, v1 row_half_mirror row_mask:0xf bank_mask:0xf bound_ctrl:1
	s_nop 1
	v_add_f32_dpp v1, v1, v1 row_mirror row_mask:0xf bank_mask:0xf bound_ctrl:1
	v_mov_b32_e32 v5, v1
	s_nop 1
	v_permlane16_swap_b32_e32 v1, v5
	v_add_f32_e32 v196, v1, v5
	s_nop 0
	v_mov_b32_dpp v1, v3 quad_perm:[1,0,3,2] row_mask:0xf bank_mask:0xf bound_ctrl:1
	v_fmac_f32_e32 v1, v4, v2
	v_mov_b32_e32 v5, v97
	v_mov_b32_e32 v197, v196
	v_add_f32_dpp v1, v1, v1 quad_perm:[2,3,0,1] row_mask:0xf bank_mask:0xf bound_ctrl:1
	s_nop 0
	v_permlane32_swap_b32_e32 v196, v197
	v_add_f32_dpp v1, v1, v1 row_half_mirror row_mask:0xf bank_mask:0xf bound_ctrl:1
	s_nop 1
	v_add_f32_dpp v1, v1, v1 row_mirror row_mask:0xf bank_mask:0xf bound_ctrl:1
	v_mov_b32_e32 v2, v1
	s_nop 1
	v_permlane16_swap_b32_e32 v1, v2
	v_add_f32_e32 v198, v1, v2
	v_ashrrev_i32_e32 v1, 31, v0
	v_lshlrev_b64 v[0:1], 10, v[0:1]
	v_lshl_add_u64 v[0:1], s[0:1], 0, v[0:1]
	s_lshl_b32 s0, s37, 7
	s_and_b32 s0, s0, 0x180
	s_lshl_b32 s54, s0, 1
	v_lshl_add_u64 v[182:183], v[0:1], 0, s[54:55]
	v_lshlrev_b32_e32 v0, 6, v195
	v_ashrrev_i32_e32 v1, 31, v0
	v_lshl_add_u64 v[0:1], v[0:1], 1, v[182:183]
	s_movk_i32 s37, 0x100
	v_lshl_add_u64 v[0:1], v[0:1], 0, v[96:97]
	v_cmp_gt_i32_e32 vcc, s37, v200
	global_load_dwordx4 v[110:113], v[0:1], off
	global_load_dwordx4 v[106:109], v[0:1], off offset:32
	global_load_dwordx4 v[102:105], v[0:1], off offset:64
	global_load_dwordx4 v[98:101], v[0:1], off offset:96
	v_cndmask_b32_e64 v0, 12, 8, vcc
	s_movk_i32 s37, 0xe0
	s_lshl_b32 s1, s30, 9
	v_cndmask_b32_e32 v1, v236, v237, vcc
	v_lshlrev_b32_e64 v0, v0, s30
	v_cmp_gt_i32_e32 vcc, s37, v200
	s_or_b32 s0, s0, s1
	v_add3_u32 v0, v1, v200, v0
	v_cndmask_b32_e64 v10, 12, 8, vcc
	s_movk_i32 s37, 0xc0
	s_mul_hi_i32 s1, s0, 0x2200
	s_mulk_i32 s0, 0x2200
	v_ashrrev_i32_e32 v1, 31, v0
	v_cndmask_b32_e32 v11, v236, v237, vcc
	v_lshlrev_b32_e64 v10, v10, s30
	v_cmp_gt_i32_e32 vcc, s37, v200
	s_add_u32 s38, s64, s0
	v_lshlrev_b64 v[0:1], 10, v[0:1]
	v_add3_u32 v10, v11, v14, v10
	v_cndmask_b32_e64 v18, 12, 8, vcc
	s_movk_i32 s37, 0xa0
	s_addc_u32 s39, s65, s1
	v_lshl_add_u64 v[0:1], s[52:53], 0, v[0:1]
	v_lshlrev_b32_e32 v2, 4, v192
	v_ashrrev_i32_e32 v11, 31, v10
	v_cndmask_b32_e32 v19, v236, v237, vcc
	v_lshlrev_b32_e64 v18, v18, s30
	v_cmp_gt_i32_e32 vcc, s37, v200
	v_lshl_add_u64 v[0:1], v[0:1], 0, s[54:55]
	v_and_b32_e32 v4, 0xf0, v2
	v_mov_b64_e32 v[30:31], s[38:39]
	v_lshlrev_b64 v[10:11], 10, v[10:11]
	v_add3_u32 v18, v19, v22, v18
	v_cndmask_b32_e64 v26, 12, 8, vcc
	v_lshl_add_u64 v[0:1], v[0:1], 0, v[4:5]
	v_mad_i64_i32 v[6:7], s[38:39], v200, s41, v[30:31]
	v_lshl_add_u64 v[10:11], s[52:53], 0, v[10:11]
	v_ashrrev_i32_e32 v19, 31, v18
	v_cndmask_b32_e32 v27, v236, v237, vcc
	v_lshlrev_b32_e64 v26, v26, s30
	global_load_dwordx4 v[0:3], v[0:1], off
	v_lshl_add_u64 v[6:7], v[6:7], 0, v[4:5]
	v_lshl_add_u64 v[10:11], v[10:11], 0, s[54:55]
	v_lshlrev_b64 v[18:19], 10, v[18:19]
	v_add3_u32 v26, v27, v32, v26
	global_load_dwordx4 v[6:9], v[6:7], off
	v_lshl_add_u64 v[10:11], v[10:11], 0, v[4:5]
	v_mad_i64_i32 v[14:15], s[38:39], v14, s41, v[30:31]
	v_lshl_add_u64 v[18:19], s[52:53], 0, v[18:19]
	v_ashrrev_i32_e32 v27, 31, v26
	global_load_dwordx4 v[10:13], v[10:11], off
	v_lshl_add_u64 v[14:15], v[14:15], 0, v[4:5]
	v_lshl_add_u64 v[18:19], v[18:19], 0, s[54:55]
	v_lshlrev_b64 v[26:27], 10, v[26:27]
	global_load_dwordx4 v[14:17], v[14:15], off
	v_lshl_add_u64 v[18:19], v[18:19], 0, v[4:5]
	v_mad_i64_i32 v[22:23], s[38:39], v22, s41, v[30:31]
	v_lshl_add_u64 v[26:27], s[52:53], 0, v[26:27]
	global_load_dwordx4 v[18:21], v[18:19], off
	v_lshl_add_u64 v[22:23], v[22:23], 0, v[4:5]
	v_lshl_add_u64 v[26:27], v[26:27], 0, s[54:55]
	global_load_dwordx4 v[22:25], v[22:23], off
	v_lshl_add_u64 v[26:27], v[26:27], 0, v[4:5]
	v_mad_i64_i32 v[30:31], s[38:39], v32, s41, v[30:31]
	global_load_dwordx4 v[26:29], v[26:27], off
	v_lshl_add_u64 v[30:31], v[30:31], 0, v[4:5]
	global_load_dwordx4 v[30:33], v[30:31], off
	s_movk_i32 s37, 0x110
	v_mul_lo_u32 v34, v200, s37
	v_add3_u32 v202, 0, v34, v4
	s_barrier
	s_waitcnt vmcnt(7)
	ds_write_b128 v202, v[0:3]
	s_waitcnt vmcnt(6)
	ds_write_b128 v202, v[6:9] offset:34816
	s_waitcnt vmcnt(5)
	ds_write_b128 v202, v[10:13] offset:8704
	s_waitcnt vmcnt(4)
	ds_write_b128 v202, v[14:17] offset:43520
	s_waitcnt vmcnt(3)
	ds_write_b128 v202, v[18:21] offset:17408
	s_waitcnt vmcnt(2)
	ds_write_b128 v202, v[22:25] offset:52224
	s_waitcnt vmcnt(1)
	ds_write_b128 v202, v[26:29] offset:26112
	s_waitcnt vmcnt(0)
	ds_write_b128 v202, v[30:33] offset:60928
	v_lshrrev_b32_e32 v1, 1, v192
	v_lshlrev_b32_e32 v2, 1, v192
	v_and_b32_e32 v0, 19, v192
	v_and_b32_e32 v1, 4, v1
	v_and_b32_e32 v2, 8, v2
	v_or3_b32 v0, v1, v0, v2
	v_mul_u32_u24_e32 v203, 0x110, v0
	v_mov_b64_e32 v[0:1], s[0:1]
	v_mad_i64_i32 v[0:1], s[0:1], v200, s41, v[0:1]
	s_add_u32 s38, s52, s54
	v_readlane_b32 s0, v255, 11
	s_addc_u32 s39, s53, 0
	v_or_b32_e32 v0, v0, v4
	v_readlane_b32 s1, v255, 12
	v_mov_b32_e32 v14, v97
	v_mov_b32_e32 v15, v97
	v_mov_b32_e32 v199, v198
	v_lshl_add_u64 v[184:185], s[38:39], 0, v[4:5]
	s_lshl_b32 s36, s36, 7
	v_lshl_add_u64 v[186:187], s[0:1], 0, v[0:1]
	v_mov_b32_e32 v0, v97
	v_mov_b32_e32 v1, v97
	v_mov_b32_e32 v2, v97
	v_mov_b32_e32 v3, v97
	v_mov_b32_e32 v4, v97
	v_mov_b32_e32 v6, v97
	v_mov_b32_e32 v7, v97
	v_mov_b32_e32 v8, v97
	v_mov_b32_e32 v9, v97
	v_mov_b32_e32 v10, v97
	v_mov_b32_e32 v11, v97
	v_mov_b32_e32 v12, v97
	v_mov_b32_e32 v13, v97
	v_mov_b64_e32 v[30:31], v[14:15]
	v_mov_b64_e32 v[46:47], v[14:15]
	v_mov_b64_e32 v[62:63], v[14:15]
	v_permlane32_swap_b32_e32 v198, v199
	s_addk_i32 s36, 0x80
	v_mov_b64_e32 v[28:29], v[12:13]
	v_mov_b64_e32 v[26:27], v[10:11]
	v_mov_b64_e32 v[24:25], v[8:9]
	v_mov_b64_e32 v[22:23], v[6:7]
	v_mov_b64_e32 v[20:21], v[4:5]
	v_mov_b64_e32 v[18:19], v[2:3]
	v_mov_b64_e32 v[16:17], v[0:1]
	v_mov_b64_e32 v[44:45], v[12:13]
	v_mov_b64_e32 v[42:43], v[10:11]
	v_mov_b64_e32 v[40:41], v[8:9]
	v_mov_b64_e32 v[38:39], v[6:7]
	v_mov_b64_e32 v[36:37], v[4:5]
	v_mov_b64_e32 v[34:35], v[2:3]
	v_mov_b64_e32 v[32:33], v[0:1]
	v_mov_b64_e32 v[60:61], v[12:13]
	v_mov_b64_e32 v[58:59], v[10:11]
	v_mov_b64_e32 v[56:57], v[8:9]
	v_mov_b64_e32 v[54:55], v[6:7]
	v_mov_b64_e32 v[52:53], v[4:5]
	v_mov_b64_e32 v[50:51], v[2:3]
	v_mov_b64_e32 v[48:49], v[0:1]
	s_mov_b32 s0, 0
	s_movk_i32 s54, 0x4000
	s_movk_i32 s41, 0x600
	v_readfirstlane_b32 s101, v226
	s_waitcnt lgkmcnt(0)
	s_barrier
	s_lshr_b32 s101, s101, 8
	s_cmp_eq_u32 s101, 0
	s_cbranch_scc1 .Latt_noprio
	s_setprio 1

; DEV void attn_tile(const Params& p, int l, int tile, char* smem, bool do_store = true) {
;     ...
;     {
;       float pe[16];
; #pragma unroll
;       for (int e = 0; e < 16; ++e) { pe[e] = __builtin_amdgcn_exp2f(s1[e] - m); lsum += pe[e]; }
; #pragma unroll
;       for (int k2 = 0; k2 < 2; ++k2) {
;         u32x4 u;
;         u[0] = pk2(pe[8 * k2 + 0], pe[8 * k2 + 1]); u[1] = pk2(pe[8 * k2 + 2], pe[8 * k2 + 3]);
;         u[2] = pk2(pe[8 * k2 + 4], pe[8 * k2 + 5]); u[3] = pk2(pe[8 * k2 + 6], pe[8 * k2 + 7]);
;         pb1[k2] = __builtin_bit_cast(bf16x8, u);
;       }
;     }
; #pragma unroll
;     for (int dt = 0; dt < 4; ++dt)
; #pragma unroll
;       for (int k2 = 0; k2 < 2; ++k2) o[dt] = __builtin_amdgcn_mfma_f32_32x32x16_bf16(vf[dt * 2 + k2], pb1[k2], o[dt], 0, 0, 0);
;     }
;     if (kt + 1 < nkt) lstore(cur ^ 1);
;     __syncthreads();
;   }
.LBB0_599:
	v_exp_f32_e32 v178, v80
	v_exp_f32_e32 v179, v81
	v_exp_f32_e32 v180, v82
	v_exp_f32_e32 v181, v83
	v_exp_f32_e32 v210, v84
	v_exp_f32_e32 v211, v85
	v_exp_f32_e32 v212, v86
	v_exp_f32_e32 v213, v87
	v_exp_f32_e32 v88, v88
	v_exp_f32_e32 v89, v89
	v_exp_f32_e32 v90, v90
	v_exp_f32_e32 v91, v91
	v_exp_f32_e32 v92, v92
	v_exp_f32_e32 v93, v93
	v_exp_f32_e32 v94, v94
	v_exp_f32_e32 v214, v95
	v_cvt_pk_bf16_f32 v80, v178, v179
	v_cvt_pk_bf16_f32 v81, v180, v181
	v_cvt_pk_bf16_f32 v82, v210, v211
	v_cvt_pk_bf16_f32 v83, v212, v213
	v_add_f32_e32 v95, v178, v209
	v_add_f32_e32 v95, v179, v95
	s_waitcnt lgkmcnt(5)
	v_mfma_f32_32x32x16_bf16 v[32:47], v[166:169], v[80:83], v[32:47]
	v_add_f32_e32 v95, v180, v95
	v_add_f32_e32 v95, v181, v95
	v_add_f32_e32 v95, v210, v95
	v_cvt_pk_bf16_f32 v84, v88, v89
	v_cvt_pk_bf16_f32 v85, v90, v91
	v_cvt_pk_bf16_f32 v86, v92, v93
	v_cvt_pk_bf16_f32 v87, v94, v214
	v_mfma_f32_32x32x16_bf16 v[48:63], v[174:177], v[80:83], v[48:63]
	v_add_f32_e32 v95, v211, v95
	v_add_f32_e32 v95, v212, v95
	v_add_f32_e32 v95, v213, v95
	v_add_f32_e32 v88, v88, v95
	v_add_f32_e32 v88, v89, v88
	v_add_f32_e32 v88, v90, v88
	s_waitcnt lgkmcnt(3)
	v_mfma_f32_32x32x16_bf16 v[16:31], v[146:149], v[80:83], v[16:31]
	v_add_f32_e32 v88, v91, v88
	v_add_f32_e32 v88, v92, v88
	v_add_f32_e32 v88, v93, v88
	v_add_f32_e32 v178, v94, v88
	s_xor_b32 s1, s1, 1
	s_mul_i32 s1, s1, 0x11000
	s_addk_i32 s31, 0x80
	s_waitcnt lgkmcnt(1)
	v_mfma_f32_32x32x16_bf16 v[0:15], v[154:157], v[80:83], v[0:15]
	s_mov_b64 s[38:39], 0x100
	s_add_i32 s0, s0, 1
	v_lshl_add_u64 v[186:187], v[186:187], 0, s[38:39]
	s_cmp_eq_u32 s36, s31
	v_mfma_f32_32x32x16_bf16 v[32:47], v[162:165], v[84:87], v[32:47]
	v_exp_f32_e32 v163, v64
	v_exp_f32_e32 v164, v65
	v_exp_f32_e32 v165, v66
	v_exp_f32_e32 v166, v67
	v_mfma_f32_32x32x16_bf16 v[48:63], v[170:173], v[84:87], v[48:63]
	v_exp_f32_e32 v167, v68
	v_exp_f32_e32 v168, v69
	v_exp_f32_e32 v169, v70
	v_exp_f32_e32 v170, v71
	v_mfma_f32_32x32x16_bf16 v[16:31], v[150:153], v[84:87], v[16:31]
	v_exp_f32_e32 v72, v72
	v_exp_f32_e32 v73, v73
	v_exp_f32_e32 v74, v74
	s_waitcnt lgkmcnt(0)
	v_mfma_f32_32x32x16_bf16 v[0:15], v[158:161], v[84:87], v[0:15]
	ds_read_b128 v[150:153], v205 offset:35008
	ds_read_b128 v[154:157], v205 offset:35040
	ds_read_b128 v[158:161], v205 offset:43712
	ds_read_b128 v[146:149], v205 offset:43744
	ds_read_b128 v[92:95], v205 offset:52416
	ds_read_b128 v[88:91], v205 offset:52448
	ds_read_b128 v[84:87], v205 offset:61120
	ds_read_b128 v[80:83], v205 offset:61152
	v_add_f32_e32 v162, v214, v178
	v_exp_f32_e32 v75, v75
	v_cvt_pk_bf16_f32 v68, v163, v164
	v_cvt_pk_bf16_f32 v69, v165, v166
	v_cvt_pk_bf16_f32 v70, v167, v168
	v_cvt_pk_bf16_f32 v71, v169, v170
	v_exp_f32_e32 v76, v76
	v_add_f32_e32 v162, v163, v162
	s_waitcnt lgkmcnt(7)
	v_mfma_f32_32x32x16_bf16 v[48:63], v[150:153], v[68:71], v[48:63]
	v_add_u32_e32 v206, s1, v202
	s_waitcnt vmcnt(7)
	ds_write_b128 v206, v[114:117]
	s_waitcnt vmcnt(6)
	ds_write_b128 v206, v[118:121] offset:34816
	v_exp_f32_e32 v77, v77
	v_add_f32_e32 v162, v164, v162
	v_exp_f32_e32 v78, v78
	v_add_f32_e32 v162, v165, v162
	v_exp_f32_e32 v79, v79
	s_waitcnt lgkmcnt(7)
	v_mfma_f32_32x32x16_bf16 v[32:47], v[158:161], v[68:71], v[32:47]
	s_waitcnt vmcnt(5)
	ds_write_b128 v206, v[122:125] offset:8704
	s_waitcnt vmcnt(4)
	ds_write_b128 v206, v[126:129] offset:43520
	v_add_f32_e32 v162, v166, v162
	v_add_f32_e32 v162, v167, v162
	v_add_f32_e32 v162, v168, v162
	v_add_f32_e32 v162, v169, v162
	v_cvt_pk_bf16_f32 v64, v72, v73
	v_cvt_pk_bf16_f32 v65, v74, v75
	v_cvt_pk_bf16_f32 v66, v76, v77
	s_waitcnt lgkmcnt(7)
	v_mfma_f32_32x32x16_bf16 v[16:31], v[92:95], v[68:71], v[16:31]
	s_waitcnt vmcnt(3)
	ds_write_b128 v206, v[130:133] offset:17408
	s_waitcnt vmcnt(2)
	ds_write_b128 v206, v[134:137] offset:52224
	v_cvt_pk_bf16_f32 v67, v78, v79
	v_add_f32_e32 v162, v170, v162
	v_add_f32_e32 v72, v72, v162
	v_add_f32_e32 v72, v73, v72
	v_add_f32_e32 v72, v74, v72
	v_add_f32_e32 v72, v75, v72
	v_add_f32_e32 v72, v76, v72
	s_waitcnt lgkmcnt(7)
	v_mfma_f32_32x32x16_bf16 v[0:15], v[84:87], v[68:71], v[0:15]
	s_waitcnt vmcnt(1)
	ds_write_b128 v206, v[138:141] offset:26112
	s_waitcnt vmcnt(0)
	ds_write_b128 v206, v[142:145] offset:60928
	v_add_f32_e32 v72, v77, v72
	v_add_f32_e32 v72, v78, v72
	v_add_f32_e32 v209, v79, v72
	v_mfma_f32_32x32x16_bf16 v[48:63], v[154:157], v[64:67], v[48:63]
	v_mfma_f32_32x32x16_bf16 v[32:47], v[146:149], v[64:67], v[32:47]
	v_mfma_f32_32x32x16_bf16 v[16:31], v[88:91], v[64:67], v[16:31]
	s_waitcnt lgkmcnt(8)
	v_mfma_f32_32x32x16_bf16 v[0:15], v[80:83], v[64:67], v[0:15]
	s_waitcnt lgkmcnt(0)
	s_barrier
	s_cbranch_scc1 .LBB0_604

; DEV void attn_tile(const Params& p, int l, int tile, char* smem, bool do_store = true) {
;     ...
;     for (int ks = 0; ks < 4; ++ks) { kf0[ks] = *(const bf16x8*)(kp + ks * 32); kf1[ks] = *(const bf16x8*)(kp + 32 * KROW + ks * 32); }
;     f32x16 s0, s1;
; #pragma unroll
;     for (int e = 0; e < 16; ++e) { s0[e] = 0.f; s1[e] = 0.f; }
; #pragma unroll
;     for (int ks = 0; ks < 4; ++ks) s0 = __builtin_amdgcn_mfma_f32_32x32x16_bf16(kf0[ks], qf[ks], s0, 0, 0, 0);
; #pragma unroll
;     for (int ks = 0; ks < 4; ++ks) s1 = __builtin_amdgcn_mfma_f32_32x32x16_bf16(kf1[ks], qf[ks], s1, 0, 0, 0);
;     bf16x8 vf[8];
; #pragma unroll
;     for (int dt = 0; dt < 4; ++dt)
; #pragma unroll
;       for (int k2 = 0; k2 < 2; ++k2) vf[dt * 2 + k2] = *(const bf16x8*)(vp + dt * 32 * KROW + (k2 * 16) * 2);
;     float mx = fmaxf(s0[0], s1[0]);
; #pragma unroll
;     for (int e = 1; e < 16; ++e) mx = fmaxf(mx, fmaxf(s0[e], s1[e]));
;     mx = xor32_max(mx);
;     const float mnew = (mx > m + 8.f) ? mx : m;
;     if (__any(mnew > m)) {
;       const float alpha = __builtin_amdgcn_exp2f(m - mnew);
;       lsum *= alpha;
; #pragma unroll
;       for (int dt = 0; dt < 4; ++dt)
; #pragma unroll
;         for (int e = 0; e < 16; ++e) o[dt][e] *= alpha;
;     }
;     m = mnew;
.Latt_a3_qk:
	s_waitcnt lgkmcnt(6)
	v_mfma_f32_32x32x16_bf16 v[80:95], v[68:71], v[110:113], 0
	s_waitcnt lgkmcnt(5)
	v_mfma_f32_32x32x16_bf16 v[80:95], v[72:75], v[106:109], v[80:95]
	s_waitcnt lgkmcnt(3)
	v_mfma_f32_32x32x16_bf16 v[80:95], v[76:79], v[102:105], v[80:95]
	v_mfma_f32_32x32x16_bf16 v[64:79], v[64:67], v[110:113], 0
	v_mfma_f32_32x32x16_bf16 v[64:79], v[212:215], v[106:109], v[64:79]
	s_waitcnt lgkmcnt(2)
	v_mfma_f32_32x32x16_bf16 v[64:79], v[216:219], v[102:105], v[64:79]
	s_waitcnt lgkmcnt(1)
	v_mfma_f32_32x32x16_bf16 v[80:95], v[146:149], v[98:101], v[80:95]
	v_mfma_f32_32x32x16_bf16 v[80:95], v[244:247], v[246:249], v[80:95]
	ds_read_b128 v[174:177], v205 offset:34816
	ds_read_b128 v[170:173], v205 offset:34848
	ds_read_b128 v[166:169], v205 offset:43520
	ds_read_b128 v[162:165], v205 offset:43552
	ds_read_b128 v[146:149], v205 offset:52224
	ds_read_b128 v[150:153], v205 offset:52256
	ds_read_b128 v[154:157], v205 offset:60928
	ds_read_b128 v[158:161], v205 offset:60960
	s_waitcnt lgkmcnt(8)
	v_mfma_f32_32x32x16_bf16 v[64:79], v[178:181], v[98:101], v[64:79]
	v_mfma_f32_32x32x16_bf16 v[64:79], v[244:247], v[246:249], v[64:79]
	s_nop 1
	v_max3_f32 v178, v80, v81, v82
	v_max3_f32 v179, v83, v84, v85
	v_max3_f32 v180, v86, v87, v88
	v_max3_f32 v181, v89, v90, v91
	v_max3_f32 v178, v178, v92, v93
	v_max3_f32 v179, v179, v94, v95
	s_nop 0
	s_nop 3
	v_max3_f32 v180, v180, v64, v65
	v_max3_f32 v181, v181, v66, v67
	v_max3_f32 v178, v178, v68, v69
	v_max3_f32 v179, v179, v70, v71
	v_max3_f32 v180, v180, v72, v73
	v_max3_f32 v181, v181, v74, v75
	v_max3_f32 v178, v178, v76, v77
	v_max3_f32 v179, v179, v78, v79
	v_max3_f32 v178, v178, v179, v180
	v_max_f32_e32 v178, v178, v181
	v_mov_b32_e32 v179, v178
	s_nop 1
	v_permlane32_swap_b32_e32 v178, v179
	v_max_f32_e32 v178, v178, v179
	v_cmp_lt_f32_e32 vcc, 0x41000000, v178
	s_cmp_eq_u32 s0, 0
	s_cbranch_scc1 .Latt_fold_first
	s_cbranch_vccz .LBB0_602
	s_branch .Latt_fold_upd
.Latt_fold_first:
	s_mov_b64 vcc, exec
.Latt_fold_upd:
	s_nop 1
	v_cndmask_b32_e32 v179, 0, v178, vcc
	v_add_f32_e32 v179, v250, v179
	v_cvt_pk_bf16_f32 v179, v179, v179
	v_and_b32_e32 v179, 0xffff0000, v179
	v_sub_f32_e32 v180, v179, v250
	v_mov_b32_e32 v250, v179
	v_sub_f32_e32 v178, 0, v180
	v_exp_f32_e32 v178, v178
	v_xor_b32_e32 v181, 0x80000000, v179
	v_lshrrev_b32_e32 v181, 16, v181
	v_and_b32_e32 v241, 63, v226
	v_cmp_gt_u32_e32 vcc, 32, v241
	s_nop 1
	v_cndmask_b32_e32 v246, 0, v181, vcc
	v_sub_f32_e32 v80, v80, v180
	v_sub_f32_e32 v81, v81, v180
	v_sub_f32_e32 v82, v82, v180
	v_sub_f32_e32 v83, v83, v180
	v_sub_f32_e32 v84, v84, v180
	v_sub_f32_e32 v85, v85, v180
	v_sub_f32_e32 v86, v86, v180
	v_sub_f32_e32 v87, v87, v180
	v_sub_f32_e32 v88, v88, v180
	v_sub_f32_e32 v89, v89, v180
	v_sub_f32_e32 v90, v90, v180
	v_sub_f32_e32 v91, v91, v180
	v_sub_f32_e32 v92, v92, v180
	v_sub_f32_e32 v93, v93, v180
	v_sub_f32_e32 v94, v94, v180
	v_sub_f32_e32 v95, v95, v180
	v_sub_f32_e32 v64, v64, v180
	v_sub_f32_e32 v65, v65, v180
	v_sub_f32_e32 v66, v66, v180
	v_sub_f32_e32 v67, v67, v180
	v_sub_f32_e32 v68, v68, v180
	v_sub_f32_e32 v69, v69, v180
	v_sub_f32_e32 v70, v70, v180
	v_sub_f32_e32 v71, v71, v180
	v_sub_f32_e32 v72, v72, v180
	v_sub_f32_e32 v73, v73, v180
	v_sub_f32_e32 v74, v74, v180
	v_sub_f32_e32 v75, v75, v180
	v_sub_f32_e32 v76, v76, v180
	v_sub_f32_e32 v77, v77, v180
	v_sub_f32_e32 v78, v78, v180
	v_sub_f32_e32 v79, v79, v180
	v_pk_mul_f32 v[62:63], v[62:63], v[178:179] op_sel_hi:[1,0]
	v_pk_mul_f32 v[60:61], v[60:61], v[178:179] op_sel_hi:[1,0]
	v_pk_mul_f32 v[58:59], v[58:59], v[178:179] op_sel_hi:[1,0]
	v_pk_mul_f32 v[56:57], v[56:57], v[178:179] op_sel_hi:[1,0]
	v_pk_mul_f32 v[54:55], v[54:55], v[178:179] op_sel_hi:[1,0]
	v_pk_mul_f32 v[52:53], v[52:53], v[178:179] op_sel_hi:[1,0]
	v_pk_mul_f32 v[50:51], v[50:51], v[178:179] op_sel_hi:[1,0]
	v_pk_mul_f32 v[48:49], v[48:49], v[178:179] op_sel_hi:[1,0]
	v_pk_mul_f32 v[46:47], v[46:47], v[178:179] op_sel_hi:[1,0]
	v_pk_mul_f32 v[44:45], v[44:45], v[178:179] op_sel_hi:[1,0]
	v_pk_mul_f32 v[42:43], v[42:43], v[178:179] op_sel_hi:[1,0]
	v_pk_mul_f32 v[40:41], v[40:41], v[178:179] op_sel_hi:[1,0]
	v_pk_mul_f32 v[38:39], v[38:39], v[178:179] op_sel_hi:[1,0]
	v_pk_mul_f32 v[36:37], v[36:37], v[178:179] op_sel_hi:[1,0]
	v_pk_mul_f32 v[34:35], v[34:35], v[178:179] op_sel_hi:[1,0]
	v_pk_mul_f32 v[32:33], v[32:33], v[178:179] op_sel_hi:[1,0]
	v_pk_mul_f32 v[30:31], v[30:31], v[178:179] op_sel_hi:[1,0]
	v_pk_mul_f32 v[28:29], v[28:29], v[178:179] op_sel_hi:[1,0]
	v_pk_mul_f32 v[26:27], v[26:27], v[178:179] op_sel_hi:[1,0]
	v_pk_mul_f32 v[24:25], v[24:25], v[178:179] op_sel_hi:[1,0]
	v_pk_mul_f32 v[22:23], v[22:23], v[178:179] op_sel_hi:[1,0]
	v_pk_mul_f32 v[20:21], v[20:21], v[178:179] op_sel_hi:[1,0]
	v_pk_mul_f32 v[18:19], v[18:19], v[178:179] op_sel_hi:[1,0]
	v_pk_mul_f32 v[16:17], v[16:17], v[178:179] op_sel_hi:[1,0]
	v_pk_mul_f32 v[14:15], v[14:15], v[178:179] op_sel_hi:[1,0]
	v_pk_mul_f32 v[12:13], v[12:13], v[178:179] op_sel_hi:[1,0]
	v_pk_mul_f32 v[10:11], v[10:11], v[178:179] op_sel_hi:[1,0]
	v_pk_mul_f32 v[8:9], v[8:9], v[178:179] op_sel_hi:[1,0]
	v_pk_mul_f32 v[6:7], v[6:7], v[178:179] op_sel_hi:[1,0]
	v_pk_mul_f32 v[4:5], v[4:5], v[178:179] op_sel_hi:[1,0]
	v_pk_mul_f32 v[2:3], v[2:3], v[178:179] op_sel_hi:[1,0]
	v_pk_mul_f32 v[0:1], v[0:1], v[178:179] op_sel_hi:[1,0]
	v_mul_f32_e32 v209, v209, v178
; DEV void attn_tile(const Params& p, int l, int tile, char* smem, bool do_store = true) {
;     ...
;     float mx = fmaxf(s0[0], s1[0]);
; #pragma unroll
;     for (int e = 1; e < 16; ++e) mx = fmaxf(mx, fmaxf(s0[e], s1[e]));
;     mx = xor32_max(mx);
;     const float mnew = (mx > m + 8.f) ? mx : m;
;     if (__any(mnew > m)) {
;       const float alpha = __builtin_amdgcn_exp2f(m - mnew);
;       lsum *= alpha;
; #pragma unroll
;       for (int dt = 0; dt < 4; ++dt)
; #pragma unroll
;         for (int e = 0; e < 16; ++e) o[dt][e] *= alpha;
;     }
;     m = mnew;
;     bf16x8 pb0[2], pb1[2];
;     {
;       float pe[16];
; #pragma unroll
;       for (int e = 0; e < 16; ++e) { pe[e] = __builtin_amdgcn_exp2f(s0[e] - m); lsum += pe[e]; }
; #pragma unroll
;       for (int k2 = 0; k2 < 2; ++k2) {
;         u32x4 u;
;         u[0] = pk2(pe[8 * k2 + 0], pe[8 * k2 + 1]); u[1] = pk2(pe[8 * k2 + 2], pe[8 * k2 + 3]);
;         u[2] = pk2(pe[8 * k2 + 4], pe[8 * k2 + 5]); u[3] = pk2(pe[8 * k2 + 6], pe[8 * k2 + 7]);
;         pb0[k2] = __builtin_bit_cast(bf16x8, u);
;       }
;     }
; #pragma unroll
;     for (int dt = 0; dt < 4; ++dt)
; #pragma unroll
;       for (int k2 = 0; k2 < 2; ++k2) o[dt] = __builtin_amdgcn_mfma_f32_32x32x16_bf16(vf[dt * 2 + k2], pb0[k2], o[dt], 0, 0, 0);
; #pragma unroll
;     for (int dt = 0; dt < 4; ++dt)
; #pragma unroll
;       for (int k2 = 0; k2 < 2; ++k2) vf[dt * 2 + k2] = *(const bf16x8*)(vp + dt * 32 * KROW + (32 + k2 * 16) * 2);
;     {
;       float pe[16];
; #pragma unroll
;       for (int e = 0; e < 16; ++e) { pe[e] = __builtin_amdgcn_exp2f(s1[e] - m); lsum += pe[e]; }
; #pragma unroll
;       for (int k2 = 0; k2 < 2; ++k2) {
;         u32x4 u;
;         u[0] = pk2(pe[8 * k2 + 0], pe[8 * k2 + 1]); u[1] = pk2(pe[8 * k2 + 2], pe[8 * k2 + 3]);
;         u[2] = pk2(pe[8 * k2 + 4], pe[8 * k2 + 5]); u[3] = pk2(pe[8 * k2 + 6], pe[8 * k2 + 7]);
;         pb1[k2] = __builtin_bit_cast(bf16x8, u);
;       }
;     }
; #pragma unroll
;     for (int dt = 0; dt < 4; ++dt)
; #pragma unroll
;       for (int k2 = 0; k2 < 2; ++k2) o[dt] = __builtin_amdgcn_mfma_f32_32x32x16_bf16(vf[dt * 2 + k2], pb1[k2], o[dt], 0, 0, 0);
.LBB0_602:
	v_exp_f32_e32 v178, v80
	v_exp_f32_e32 v179, v81
	v_exp_f32_e32 v180, v82
	v_exp_f32_e32 v181, v83
	v_exp_f32_e32 v208, v84
	v_exp_f32_e32 v212, v85
	v_exp_f32_e32 v213, v86
	v_exp_f32_e32 v214, v87
	v_exp_f32_e32 v88, v88
	v_exp_f32_e32 v89, v89
	v_exp_f32_e32 v90, v90
	v_exp_f32_e32 v91, v91
	v_exp_f32_e32 v92, v92
	v_exp_f32_e32 v93, v93
	v_exp_f32_e32 v94, v94
	v_exp_f32_e32 v215, v95
	v_cvt_pk_bf16_f32 v80, v178, v179
	v_cvt_pk_bf16_f32 v81, v180, v181
	v_cvt_pk_bf16_f32 v82, v208, v212
	v_cvt_pk_bf16_f32 v83, v213, v214
	v_add_f32_e32 v95, v178, v209
	v_add_f32_e32 v95, v179, v95
	s_waitcnt lgkmcnt(5)
	v_mfma_f32_32x32x16_bf16 v[32:47], v[166:169], v[80:83], v[32:47]
	v_add_f32_e32 v95, v180, v95
	v_add_f32_e32 v95, v181, v95
	v_add_f32_e32 v95, v208, v95
	v_add_f32_e32 v95, v212, v95
	v_cvt_pk_bf16_f32 v84, v88, v89
	v_cvt_pk_bf16_f32 v85, v90, v91
	v_cvt_pk_bf16_f32 v86, v92, v93
	v_cvt_pk_bf16_f32 v87, v94, v215
	v_add_f32_e32 v95, v213, v95
	v_mfma_f32_32x32x16_bf16 v[48:63], v[174:177], v[80:83], v[48:63]
	v_add_f32_e32 v95, v214, v95
	v_add_f32_e32 v88, v88, v95
	v_add_f32_e32 v88, v89, v88
	v_add_f32_e32 v88, v90, v88
	v_add_f32_e32 v88, v91, v88
	v_add_f32_e32 v88, v92, v88
	s_waitcnt lgkmcnt(4)
	v_mfma_f32_32x32x16_bf16 v[32:47], v[162:165], v[84:87], v[32:47]
	v_exp_f32_e32 v163, v64
	v_exp_f32_e32 v164, v65
	v_exp_f32_e32 v165, v66
	v_exp_f32_e32 v166, v67
	s_waitcnt lgkmcnt(3)
	v_mfma_f32_32x32x16_bf16 v[16:31], v[146:149], v[80:83], v[16:31]
	v_exp_f32_e32 v167, v68
	v_exp_f32_e32 v168, v69
	v_add_f32_e32 v88, v93, v88
	v_exp_f32_e32 v169, v70
	s_waitcnt lgkmcnt(1)
	v_mfma_f32_32x32x16_bf16 v[0:15], v[154:157], v[80:83], v[0:15]
	v_add_f32_e32 v178, v94, v88
	v_add_f32_e32 v162, v215, v178
	v_add_f32_e32 v162, v163, v162
	v_add_f32_e32 v162, v164, v162
	v_add_f32_e32 v162, v165, v162
	v_add_f32_e32 v162, v166, v162
	v_mfma_f32_32x32x16_bf16 v[48:63], v[170:173], v[84:87], v[48:63]
	v_exp_f32_e32 v170, v71
	v_exp_f32_e32 v72, v72
	v_exp_f32_e32 v73, v73
	v_exp_f32_e32 v74, v74
	v_mfma_f32_32x32x16_bf16 v[16:31], v[150:153], v[84:87], v[16:31]
	v_exp_f32_e32 v75, v75
	v_exp_f32_e32 v76, v76
	v_exp_f32_e32 v77, v77
	s_waitcnt lgkmcnt(0)
	v_mfma_f32_32x32x16_bf16 v[0:15], v[158:161], v[84:87], v[0:15]
	ds_read_b128 v[80:83], v205 offset:34880
	ds_read_b128 v[84:87], v205 offset:34912
	ds_read_b128 v[88:91], v205 offset:43584
	ds_read_b128 v[92:95], v205 offset:43616
	ds_read_b128 v[146:149], v205 offset:52288
	ds_read_b128 v[150:153], v205 offset:52320
	ds_read_b128 v[154:157], v205 offset:60992
	ds_read_b128 v[158:161], v205 offset:61024
	v_add_f32_e32 v162, v167, v162
	v_exp_f32_e32 v78, v78
	v_add_f32_e32 v162, v168, v162
	v_exp_f32_e32 v79, v79
	v_cvt_pk_bf16_f32 v64, v163, v164
	v_cvt_pk_bf16_f32 v65, v165, v166
	v_cvt_pk_bf16_f32 v66, v167, v168
	v_cvt_pk_bf16_f32 v67, v169, v170
	v_add_f32_e32 v162, v169, v162
	v_add_f32_e32 v162, v170, v162
	s_waitcnt lgkmcnt(7)
	v_mfma_f32_32x32x16_bf16 v[48:63], v[80:83], v[64:67], v[48:63]
	v_cvt_pk_bf16_f32 v68, v72, v73
	v_add_f32_e32 v72, v72, v162
	v_add_f32_e32 v72, v73, v72
	v_add_f32_e32 v72, v74, v72
	v_add_f32_e32 v72, v75, v72
	v_add_f32_e32 v72, v76, v72
	v_add_f32_e32 v72, v77, v72
	s_waitcnt lgkmcnt(5)
	v_mfma_f32_32x32x16_bf16 v[32:47], v[88:91], v[64:67], v[32:47]
	v_cvt_pk_bf16_f32 v69, v74, v75
	v_cvt_pk_bf16_f32 v70, v76, v77
	v_cvt_pk_bf16_f32 v71, v78, v79
	v_add_f32_e32 v72, v78, v72
	v_add_f32_e32 v209, v79, v72
	s_waitcnt lgkmcnt(3)
	v_mfma_f32_32x32x16_bf16 v[16:31], v[146:149], v[64:67], v[16:31]
	s_waitcnt lgkmcnt(1)
	v_mfma_f32_32x32x16_bf16 v[0:15], v[154:157], v[64:67], v[0:15]
	v_mfma_f32_32x32x16_bf16 v[48:63], v[84:87], v[68:71], v[48:63]
	v_mfma_f32_32x32x16_bf16 v[32:47], v[92:95], v[68:71], v[32:47]
	v_mfma_f32_32x32x16_bf16 v[16:31], v[150:153], v[68:71], v[16:31]
	s_waitcnt lgkmcnt(0)
	v_mfma_f32_32x32x16_bf16 v[0:15], v[158:161], v[68:71], v[0:15]
	ds_read_b128 v[64:67], v210 offset:26112
	ds_read_b128 v[68:71], v210 offset:17408
	ds_read_b128 v[72:75], v210 offset:17440
	ds_read_b128 v[212:215], v210 offset:26144
	ds_read_b128 v[76:79], v210 offset:17472
	ds_read_b128 v[216:219], v210 offset:26176
	ds_read_b128 v[146:149], v210 offset:17504
	ds_read_b128 v[178:181], v210 offset:26208
	s_waitcnt lgkmcnt(6)
	v_mfma_f32_32x32x16_bf16 v[80:95], v[68:71], v[110:113], 0
	s_waitcnt lgkmcnt(5)
	v_mfma_f32_32x32x16_bf16 v[80:95], v[72:75], v[106:109], v[80:95]
	s_waitcnt lgkmcnt(3)
	v_mfma_f32_32x32x16_bf16 v[80:95], v[76:79], v[102:105], v[80:95]
	v_mfma_f32_32x32x16_bf16 v[64:79], v[64:67], v[110:113], 0
	v_mfma_f32_32x32x16_bf16 v[64:79], v[212:215], v[106:109], v[64:79]
	s_waitcnt lgkmcnt(2)
	v_mfma_f32_32x32x16_bf16 v[64:79], v[216:219], v[102:105], v[64:79]
	s_waitcnt lgkmcnt(1)
	v_mfma_f32_32x32x16_bf16 v[80:95], v[146:149], v[98:101], v[80:95]
	v_mfma_f32_32x32x16_bf16 v[80:95], v[244:247], v[246:249], v[80:95]
	ds_read_b128 v[174:177], v205 offset:34944
	ds_read_b128 v[170:173], v205 offset:34976
	ds_read_b128 v[166:169], v205 offset:43648
	ds_read_b128 v[162:165], v205 offset:43680
	ds_read_b128 v[146:149], v205 offset:52352
	ds_read_b128 v[150:153], v205 offset:52384
	ds_read_b128 v[154:157], v205 offset:61056
	ds_read_b128 v[158:161], v205 offset:61088
	s_waitcnt lgkmcnt(8)
	v_mfma_f32_32x32x16_bf16 v[64:79], v[178:181], v[98:101], v[64:79]
	v_mfma_f32_32x32x16_bf16 v[64:79], v[244:247], v[246:249], v[64:79]
	s_nop 3
	s_nop 0
	s_branch .LBB0_599
; DEV void attn_tile(const Params& p, int l, int tile, char* smem, bool do_store = true) {
;     ...
;     for (int h2 = 0; h2 < 2; ++h2) {
;     const char* kp = Ks + (h2 * 64 + kos) * KROW + (map * 64 + hh * 8) * 2;
;     const char* vp = Vs + ql * KROW + hh * 16 + h2 * 128;
;     bf16x8 kf0[4], kf1[4];
; #pragma unroll
;     for (int ks = 0; ks < 4; ++ks) { kf0[ks] = *(const bf16x8*)(kp + ks * 32); kf1[ks] = *(const bf16x8*)(kp + 32 * KROW + ks * 32); }
;     f32x16 s0, s1;
; #pragma unroll
;     for (int e = 0; e < 16; ++e) { s0[e] = 0.f; s1[e] = 0.f; }
; #pragma unroll
;     for (int ks = 0; ks < 4; ++ks) s0 = __builtin_amdgcn_mfma_f32_32x32x16_bf16(kf0[ks], qf[ks], s0, 0, 0, 0);
; #pragma unroll
;     for (int ks = 0; ks < 4; ++ks) s1 = __builtin_amdgcn_mfma_f32_32x32x16_bf16(kf1[ks], qf[ks], s1, 0, 0, 0);
;     bf16x8 vf[8];
; #pragma unroll
;     for (int dt = 0; dt < 4; ++dt)
; #pragma unroll
;       for (int k2 = 0; k2 < 2; ++k2) vf[dt * 2 + k2] = *(const bf16x8*)(vp + dt * 32 * KROW + (k2 * 16) * 2);
;     float mx = fmaxf(s0[0], s1[0]);
; #pragma unroll
;     for (int e = 1; e < 16; ++e) mx = fmaxf(mx, fmaxf(s0[e], s1[e]));
;     mx = xor32_max(mx);
;     const float mnew = (mx > m + 8.f) ? mx : m;
;     if (__any(mnew > m)) {
;       const float alpha = __builtin_amdgcn_exp2f(m - mnew);
;       lsum *= alpha;
; #pragma unroll
;       for (int dt = 0; dt < 4; ++dt)
; #pragma unroll
;         for (int e = 0; e < 16; ++e) o[dt][e] *= alpha;
;     }
;     m = mnew;
.LBB0_604:
	v_mov_b32_e32 v208, v250
	s_bitcmp1_b32 s0, 0
	s_cselect_b32 s0, 0x11000, 0
	s_add_i32 s0, s0, 0
	v_add_u32_e32 v64, s0, v204
	v_add_u32_e32 v147, v64, v203
	ds_read_b128 v[64:67], v147
	ds_read_b128 v[68:71], v147 offset:32
	s_waitcnt lgkmcnt(1)
	v_mfma_f32_32x32x16_bf16 v[80:95], v[64:67], v[110:113], 0
	ds_read_b128 v[64:67], v147 offset:64
	ds_read_b128 v[148:151], v147 offset:96
	s_waitcnt lgkmcnt(2)
	v_mfma_f32_32x32x16_bf16 v[80:95], v[68:71], v[106:109], v[80:95]
	s_waitcnt lgkmcnt(1)
	v_mfma_f32_32x32x16_bf16 v[80:95], v[64:67], v[102:105], v[80:95]
	ds_read_b128 v[64:67], v147 offset:8704
	ds_read_b128 v[114:117], v147 offset:8736
	s_waitcnt lgkmcnt(1)
	v_mfma_f32_32x32x16_bf16 v[64:79], v[64:67], v[110:113], 0
	s_waitcnt lgkmcnt(0)
	v_mfma_f32_32x32x16_bf16 v[64:79], v[114:117], v[106:109], v[64:79]
	ds_read_b128 v[114:117], v147 offset:8768
	ds_read_b128 v[118:121], v147 offset:8800
	s_waitcnt lgkmcnt(1)
	v_mfma_f32_32x32x16_bf16 v[64:79], v[114:117], v[102:105], v[64:79]
	v_add_u32_e32 v114, s0, v201
	v_add_u32_e32 v146, v114, v96
	ds_read_b128 v[142:145], v146 offset:34816
	ds_read_b128 v[130:133], v146 offset:34848
	s_waitcnt lgkmcnt(2)
	v_mfma_f32_32x32x16_bf16 v[64:79], v[118:121], v[98:101], v[64:79]
	ds_read_b128 v[138:141], v146 offset:43520
	ds_read_b128 v[134:137], v146 offset:43552
	ds_read_b128 v[122:125], v146 offset:52224
	ds_read_b128 v[126:129], v146 offset:52256
	ds_read_b128 v[118:121], v146 offset:60928
	ds_read_b128 v[114:117], v146 offset:60960
	s_nop 5
	v_max_f32_e32 v152, v65, v65
	v_mfma_f32_32x32x16_bf16 v[80:95], v[148:151], v[98:101], v[80:95]
	v_max_f32_e32 v149, v66, v66
	s_nop 10
	v_max_f32_e32 v148, v81, v81
	v_max_f32_e32 v150, v82, v82
	v_max_f32_e32 v148, v148, v152
	v_max_f32_e32 v149, v150, v149
	v_max_f32_e32 v150, v67, v67
	v_max_f32_e32 v151, v83, v83
	v_max3_f32 v148, v80, v64, v148
	v_max_f32_e32 v150, v151, v150
	v_max3_f32 v148, v148, v149, v150
	v_max_f32_e32 v149, v68, v68
	v_max_f32_e32 v150, v84, v84
	v_max_f32_e32 v149, v150, v149
	v_max_f32_e32 v150, v69, v69
	v_max_f32_e32 v151, v85, v85
	v_max_f32_e32 v150, v151, v150
	v_max3_f32 v148, v148, v149, v150
	v_max_f32_e32 v149, v70, v70
	v_max_f32_e32 v150, v86, v86
	v_max_f32_e32 v149, v150, v149
	v_max_f32_e32 v150, v71, v71
	v_max_f32_e32 v151, v87, v87
	v_max_f32_e32 v150, v151, v150
	v_max3_f32 v148, v148, v149, v150
	v_max_f32_e32 v149, v72, v72
	v_max_f32_e32 v150, v88, v88
	v_max_f32_e32 v149, v150, v149
	v_max_f32_e32 v150, v73, v73
	v_max_f32_e32 v151, v89, v89
	v_max_f32_e32 v150, v151, v150
	v_max3_f32 v148, v148, v149, v150
	v_max_f32_e32 v149, v74, v74
	v_max_f32_e32 v150, v90, v90
	v_max_f32_e32 v149, v150, v149
	v_max_f32_e32 v150, v75, v75
	v_max_f32_e32 v151, v91, v91
	v_max_f32_e32 v150, v151, v150
	v_max3_f32 v148, v148, v149, v150
	v_max_f32_e32 v149, v76, v76
	v_max_f32_e32 v150, v92, v92
	v_max_f32_e32 v149, v150, v149
	v_max_f32_e32 v150, v77, v77
	v_max_f32_e32 v151, v93, v93
	v_max_f32_e32 v150, v151, v150
	v_max3_f32 v148, v148, v149, v150
	v_max_f32_e32 v149, v78, v78
	v_max_f32_e32 v150, v94, v94
	v_max_f32_e32 v149, v150, v149
	v_max_f32_e32 v150, v79, v79
	v_max_f32_e32 v151, v95, v95
	v_max_f32_e32 v150, v151, v150
	v_max3_f32 v148, v148, v149, v150
	v_mov_b32_e32 v149, v148
	s_nop 1
	v_permlane32_swap_b32_e32 v148, v149
	v_max_f32_e32 v149, v149, v149
	v_max_f32_e32 v148, v148, v148
	v_max_f32_e32 v148, v148, v149
	v_add_f32_e32 v149, 0x41000000, v208
	v_cmp_gt_f32_e32 vcc, v148, v149
	s_nop 1
	v_cndmask_b32_e32 v148, v208, v148, vcc
	v_cmp_gt_f32_e32 vcc, v148, v208
	s_cbranch_vccz .LBB0_606
	v_sub_f32_e32 v149, v208, v148
	v_exp_f32_e32 v150, v149
	s_nop 0
	v_pk_mul_f32 v[62:63], v[62:63], v[150:151] op_sel_hi:[1,0]
	v_pk_mul_f32 v[60:61], v[60:61], v[150:151] op_sel_hi:[1,0]
	v_pk_mul_f32 v[58:59], v[58:59], v[150:151] op_sel_hi:[1,0]
	v_pk_mul_f32 v[56:57], v[56:57], v[150:151] op_sel_hi:[1,0]
	v_pk_mul_f32 v[54:55], v[54:55], v[150:151] op_sel_hi:[1,0]
	v_pk_mul_f32 v[52:53], v[52:53], v[150:151] op_sel_hi:[1,0]
	v_pk_mul_f32 v[50:51], v[50:51], v[150:151] op_sel_hi:[1,0]
	v_pk_mul_f32 v[48:49], v[48:49], v[150:151] op_sel_hi:[1,0]
	v_pk_mul_f32 v[46:47], v[46:47], v[150:151] op_sel_hi:[1,0]
	v_pk_mul_f32 v[44:45], v[44:45], v[150:151] op_sel_hi:[1,0]
	v_pk_mul_f32 v[42:43], v[42:43], v[150:151] op_sel_hi:[1,0]
	v_pk_mul_f32 v[40:41], v[40:41], v[150:151] op_sel_hi:[1,0]
	v_pk_mul_f32 v[38:39], v[38:39], v[150:151] op_sel_hi:[1,0]
	v_pk_mul_f32 v[36:37], v[36:37], v[150:151] op_sel_hi:[1,0]
	v_pk_mul_f32 v[34:35], v[34:35], v[150:151] op_sel_hi:[1,0]
	v_pk_mul_f32 v[32:33], v[32:33], v[150:151] op_sel_hi:[1,0]
	v_pk_mul_f32 v[30:31], v[30:31], v[150:151] op_sel_hi:[1,0]
	v_pk_mul_f32 v[28:29], v[28:29], v[150:151] op_sel_hi:[1,0]
	v_pk_mul_f32 v[26:27], v[26:27], v[150:151] op_sel_hi:[1,0]
	v_pk_mul_f32 v[24:25], v[24:25], v[150:151] op_sel_hi:[1,0]
	v_pk_mul_f32 v[22:23], v[22:23], v[150:151] op_sel_hi:[1,0]
	v_pk_mul_f32 v[20:21], v[20:21], v[150:151] op_sel_hi:[1,0]
	v_pk_mul_f32 v[18:19], v[18:19], v[150:151] op_sel_hi:[1,0]
	v_pk_mul_f32 v[16:17], v[16:17], v[150:151] op_sel_hi:[1,0]
	v_pk_mul_f32 v[14:15], v[14:15], v[150:151] op_sel_hi:[1,0]
	v_pk_mul_f32 v[12:13], v[12:13], v[150:151] op_sel_hi:[1,0]
	v_pk_mul_f32 v[10:11], v[10:11], v[150:151] op_sel_hi:[1,0]
	v_pk_mul_f32 v[8:9], v[8:9], v[150:151] op_sel_hi:[1,0]
	v_pk_mul_f32 v[6:7], v[6:7], v[150:151] op_sel_hi:[1,0]
	v_pk_mul_f32 v[4:5], v[4:5], v[150:151] op_sel_hi:[1,0]
	v_pk_mul_f32 v[2:3], v[2:3], v[150:151] op_sel_hi:[1,0]
	v_pk_mul_f32 v[0:1], v[0:1], v[150:151] op_sel_hi:[1,0]
	v_mul_f32_e32 v209, v209, v150
